# gate_prompt row statistics: next trip's row loads requested one trip ahead
# speedup vs baseline: 1.1002x; 1.0070x over previous
; #define LAS __attribute__((address_space(3)))
; __device__ __forceinline__ void gate_prompt_item(LAS unsigned char* lds, const bf16_t* z, bf16_t* mix, const float* w_s, const float* b_s,
;                                                  const float* lnv_g, const float* lnv_b, int item, int tid) {
;     ...
;     const size_t tok0 = (size_t)b * SEQL + n * 128;
;     LAS float* stat = (LAS float*)lds;
;     LAS unsigned char* vn = lds + 1024;
; #pragma unroll 2
;     for (int r = 0; r < 16; ++r) {
;         const int row = 16 * wave + r;
;         const bf16_t* vp = z + (tok0 + row) * EIN + 3328 + lane * 16;
;         const u32x4 a = *(const u32x4*)vp, c = *(const u32x4*)(vp + 8);
.LBB0_907:
	s_ashr_i32 s82, s19, 7
	s_bfe_u32 s80, s19, 0x50002
	s_ashr_i32 s83, s82, 31
	s_mul_i32 s8, s82, 0x2a00000
	s_mul_i32 s80, s80, 0x150000
	s_mul_hi_i32 s9, s82, 0x2a00000
	s_add_u32 s8, s8, s80
	s_addc_u32 s9, s9, 0
	v_lshl_add_u64 v[2:3], v[48:49], 0, s[8:9]
	s_mov_b64 s[84:85], 0
	v_add_co_u32_e32 v250, vcc, 0x13e09a00, v2
	s_nop 1
	v_addc_co_u32_e32 v251, vcc, 0, v3, vcc
	global_load_dwordx4 v[226:229], v[250:251], off
	global_load_dwordx4 v[230:233], v[250:251], off offset:16
	v_add_co_u32_e32 v250, vcc, 0x2a00, v250
	s_nop 1
	v_addc_co_u32_e32 v251, vcc, 0, v251, vcc
	global_load_dwordx4 v[234:237], v[250:251], off
	global_load_dwordx4 v[238:241], v[250:251], off offset:16
	v_mov_b32_e32 v0, v126
	s_branch .LBB0_909

; __device__ __forceinline__ float bf_lo(unsigned w) { return __uint_as_float(w << 16); }
; __device__ __forceinline__ float bf_hi(unsigned w) { return __uint_as_float(w & 0xffff0000u); }
; __device__ __forceinline__ void gate_prompt_item(LAS unsigned char* lds, const bf16_t* z, bf16_t* mix, const float* w_s, const float* b_s,
;                                                  const float* lnv_g, const float* lnv_b, int item, int tid) {
;     ...
;     for (int r = 0; r < 16; ++r) {
;         const int row = 16 * wave + r;
;         const bf16_t* vp = z + (tok0 + row) * EIN + 3328 + lane * 16;
;         const u32x4 a = *(const u32x4*)vp, c = *(const u32x4*)(vp + 8);
;         float v[16] = {bf_lo(a.x), bf_hi(a.x), bf_lo(a.y), bf_hi(a.y), bf_lo(a.z), bf_hi(a.z), bf_lo(a.w), bf_hi(a.w),
;                        bf_lo(c.x), bf_hi(c.x), bf_lo(c.y), bf_hi(c.y), bf_lo(c.z), bf_hi(c.z), bf_lo(c.w), bf_hi(c.w)};
;         float s = 0.f;
; #pragma unroll
;         for (int e = 0; e < 16; ++e) s += v[e];
;         const float mean = wave_sum(s) * (1.0f / 1024.0f);
;         float q = 0.f;
; #pragma unroll
;         for (int e = 0; e < 16; ++e) { const float d = v[e] - mean; q += d * d; }
;         const float rstd = rsqrtf(wave_sum(q) * (1.0f / 1024.0f) + EPSN);
;         if (lane == 0) { stat[row * 2] = mean; stat[row * 2 + 1] = rstd; }
.LBB0_909:
	v_lshl_add_u64 v[4:5], v[2:3], 0, s[84:85]
	s_waitcnt lgkmcnt(0)
	s_waitcnt vmcnt(0)
	v_mov_b32_e32 v6, v226
	v_mov_b32_e32 v7, v227
	v_mov_b32_e32 v8, v228
	v_mov_b32_e32 v9, v229
	v_mov_b32_e32 v10, v230
	v_mov_b32_e32 v11, v231
	v_mov_b32_e32 v12, v232
	v_mov_b32_e32 v13, v233
	v_mov_b32_e32 v242, v234
	v_mov_b32_e32 v243, v235
	v_mov_b32_e32 v244, v236
	v_mov_b32_e32 v245, v237
	v_mov_b32_e32 v246, v238
	v_mov_b32_e32 v247, v239
	v_mov_b32_e32 v248, v240
	v_mov_b32_e32 v249, v241
	s_cmp_eq_u32 s84, 0x24c00
	s_cbranch_scc1 .Lgp_nopf
	v_add_co_u32_e32 v250, vcc, 0x13e0ee00, v4
	s_nop 1
	v_addc_co_u32_e32 v251, vcc, 0, v5, vcc
	global_load_dwordx4 v[226:229], v[250:251], off
	global_load_dwordx4 v[230:233], v[250:251], off offset:16
	v_add_co_u32_e32 v250, vcc, 0x2a00, v250
	s_nop 1
	v_addc_co_u32_e32 v251, vcc, 0, v251, vcc
	global_load_dwordx4 v[234:237], v[250:251], off
	global_load_dwordx4 v[238:241], v[250:251], off offset:16
.Lgp_nopf:
	v_lshlrev_b32_e32 v14, 16, v6
	v_and_b32_e32 v15, 0xffff0000, v6
	v_add_f32_e32 v6, 0, v14
	v_lshlrev_b32_e32 v16, 16, v7
	v_add_f32_e32 v6, v6, v15
	v_and_b32_e32 v7, 0xffff0000, v7
	v_add_f32_e32 v6, v6, v16
	v_lshlrev_b32_e32 v17, 16, v8
	v_add_f32_e32 v6, v6, v7
	v_and_b32_e32 v8, 0xffff0000, v8
	v_add_f32_e32 v6, v6, v17
	v_lshlrev_b32_e32 v18, 16, v9
	v_add_f32_e32 v6, v6, v8
	v_and_b32_e32 v9, 0xffff0000, v9
	v_add_f32_e32 v6, v6, v18
	v_lshlrev_b32_e32 v19, 16, v10
	v_add_f32_e32 v6, v6, v9
	v_and_b32_e32 v10, 0xffff0000, v10
	v_add_f32_e32 v6, v6, v19
	v_lshlrev_b32_e32 v20, 16, v11
	v_add_f32_e32 v6, v6, v10
	v_and_b32_e32 v11, 0xffff0000, v11
	v_add_f32_e32 v6, v6, v20
	v_lshlrev_b32_e32 v21, 16, v12
	v_add_f32_e32 v6, v6, v11
	v_and_b32_e32 v12, 0xffff0000, v12
	v_add_f32_e32 v6, v6, v21
	v_lshlrev_b32_e32 v22, 16, v13
	v_add_f32_e32 v6, v6, v12
	v_and_b32_e32 v13, 0xffff0000, v13
	v_add_f32_e32 v6, v6, v22
	v_add_f32_e32 v6, v6, v13
	s_waitcnt lgkmcnt(0)
	s_nop 1
	v_add_f32_dpp v6, v6, v6 quad_perm:[1,0,3,2] row_mask:0xf bank_mask:0xf
	s_nop 1
	v_add_f32_dpp v6, v6, v6 quad_perm:[2,3,0,1] row_mask:0xf bank_mask:0xf
	s_nop 1
	v_add_f32_dpp v6, v6, v6 row_half_mirror row_mask:0xf bank_mask:0xf
	s_nop 1
	v_add_f32_dpp v6, v6, v6 row_mirror row_mask:0xf bank_mask:0xf
	s_nop 1
	v_add_f32_dpp v6, v6, v6 row_bcast:15 row_mask:0xa bank_mask:0xf
	s_nop 1
	v_add_f32_dpp v6, v6, v6 row_bcast:31 row_mask:0xc bank_mask:0xf
	s_nop 1
	v_readlane_b32 s100, v6, 63
	s_nop 1
	v_mov_b32_e32 v6, s100
	v_fmac_f32_e32 v15, 0xba800000, v6
	v_fmac_f32_e32 v14, 0xba800000, v6
	v_mul_f32_e32 v15, v15, v15
	v_fmac_f32_e32 v16, 0xba800000, v6
	v_fmac_f32_e32 v15, v14, v14
	v_fmac_f32_e32 v7, 0xba800000, v6
	v_fmac_f32_e32 v15, v16, v16
	v_fmac_f32_e32 v17, 0xba800000, v6
	v_fmac_f32_e32 v15, v7, v7
	v_fmac_f32_e32 v8, 0xba800000, v6
	v_fmac_f32_e32 v15, v17, v17
	v_fmac_f32_e32 v18, 0xba800000, v6
	v_fmac_f32_e32 v15, v8, v8
	v_fmac_f32_e32 v9, 0xba800000, v6
	v_fmac_f32_e32 v15, v18, v18
	v_fmac_f32_e32 v19, 0xba800000, v6
	v_fmac_f32_e32 v15, v9, v9
	v_fmac_f32_e32 v10, 0xba800000, v6
	v_fmac_f32_e32 v15, v19, v19
	v_fmac_f32_e32 v20, 0xba800000, v6
	v_fmac_f32_e32 v15, v10, v10
	v_fmac_f32_e32 v11, 0xba800000, v6
	v_fmac_f32_e32 v15, v20, v20
	v_fmac_f32_e32 v21, 0xba800000, v6
	v_fmac_f32_e32 v15, v11, v11
	v_fmac_f32_e32 v12, 0xba800000, v6
	v_fmac_f32_e32 v15, v21, v21
	v_fmac_f32_e32 v22, 0xba800000, v6
	v_fmac_f32_e32 v15, v12, v12
	v_fmac_f32_e32 v15, v22, v22
	v_fmac_f32_e32 v13, 0xba800000, v6
	v_fmac_f32_e32 v15, v13, v13
	ds_bpermute_b32 v7, v47, v15
	s_waitcnt lgkmcnt(0)
	v_add_f32_e32 v7, v15, v7
	ds_bpermute_b32 v8, v120, v7
	s_waitcnt lgkmcnt(0)
	v_add_f32_e32 v7, v7, v8
	ds_bpermute_b32 v8, v121, v7
	s_waitcnt lgkmcnt(0)
	v_add_f32_e32 v7, v7, v8
	ds_bpermute_b32 v8, v122, v7
	s_waitcnt lgkmcnt(0)
	v_add_f32_e32 v7, v7, v8
	ds_bpermute_b32 v8, v123, v7
	s_waitcnt lgkmcnt(0)
	v_add_f32_e32 v7, v7, v8
	ds_bpermute_b32 v8, v124, v7
	s_and_saveexec_b64 s[8:9], s[4:5]
	s_cbranch_execz .LBB0_911
	s_waitcnt lgkmcnt(0)
	v_add_f32_e32 v7, v7, v8
	v_fmamk_f32 v7, v7, 0x3a800000, v138
	v_mul_f32_e32 v8, 0x4b800000, v7
	v_cmp_gt_f32_e32 vcc, s59, v7
	v_mul_f32_e32 v6, 0x3a800000, v6
	s_nop 0
	v_cndmask_b32_e32 v7, v7, v8, vcc
	v_rsq_f32_e32 v7, v7
	s_nop 0
	v_mul_f32_e32 v8, 0x45800000, v7
	v_cndmask_b32_e32 v7, v7, v8, vcc
	ds_write_b64 v0, v[6:7]
; __device__ __forceinline__ float bf_lo(unsigned w) { return __uint_as_float(w << 16); }
; __device__ __forceinline__ float bf_hi(unsigned w) { return __uint_as_float(w & 0xffff0000u); }
; __device__ __forceinline__ void gate_prompt_item(LAS unsigned char* lds, const bf16_t* z, bf16_t* mix, const float* w_s, const float* b_s,
;                                                  const float* lnv_g, const float* lnv_b, int item, int tid) {
;     ...
;     for (int r = 0; r < 16; ++r) {
;         const int row = 16 * wave + r;
;         const bf16_t* vp = z + (tok0 + row) * EIN + 3328 + lane * 16;
;         const u32x4 a = *(const u32x4*)vp, c = *(const u32x4*)(vp + 8);
;         float v[16] = {bf_lo(a.x), bf_hi(a.x), bf_lo(a.y), bf_hi(a.y), bf_lo(a.z), bf_hi(a.z), bf_lo(a.w), bf_hi(a.w),
;                        bf_lo(c.x), bf_hi(c.x), bf_lo(c.y), bf_hi(c.y), bf_lo(c.z), bf_hi(c.z), bf_lo(c.w), bf_hi(c.w)};
;         float s = 0.f;
; #pragma unroll
;         for (int e = 0; e < 16; ++e) s += v[e];
;         const float mean = wave_sum(s) * (1.0f / 1024.0f);
;         float q = 0.f;
; #pragma unroll
;         for (int e = 0; e < 16; ++e) { const float d = v[e] - mean; q += d * d; }
;         const float rstd = rsqrtf(wave_sum(q) * (1.0f / 1024.0f) + EPSN);
;         if (lane == 0) { stat[row * 2] = mean; stat[row * 2 + 1] = rstd; }
;     }
.LBB0_911:
	s_or_b64 exec, exec, s[8:9]
	s_waitcnt lgkmcnt(0)
	v_mov_b32_e32 v6, v242
	v_mov_b32_e32 v7, v243
	v_mov_b32_e32 v8, v244
	v_mov_b32_e32 v9, v245
	v_mov_b32_e32 v10, v246
	v_mov_b32_e32 v11, v247
	v_mov_b32_e32 v12, v248
	v_mov_b32_e32 v13, v249
	v_lshlrev_b32_e32 v5, 16, v6
	v_and_b32_e32 v6, 0xffff0000, v6
	v_add_f32_e32 v4, 0, v5
	v_lshlrev_b32_e32 v14, 16, v7
	v_add_f32_e32 v4, v4, v6
	v_and_b32_e32 v7, 0xffff0000, v7
	v_add_f32_e32 v4, v4, v14
	v_lshlrev_b32_e32 v15, 16, v8
	v_add_f32_e32 v4, v4, v7
	v_and_b32_e32 v8, 0xffff0000, v8
	v_add_f32_e32 v4, v4, v15
	v_lshlrev_b32_e32 v16, 16, v9
	v_add_f32_e32 v4, v4, v8
	v_and_b32_e32 v9, 0xffff0000, v9
	v_add_f32_e32 v4, v4, v16
	v_lshlrev_b32_e32 v17, 16, v10
	v_add_f32_e32 v4, v4, v9
	v_and_b32_e32 v10, 0xffff0000, v10
	v_add_f32_e32 v4, v4, v17
	v_lshlrev_b32_e32 v18, 16, v11
	v_add_f32_e32 v4, v4, v10
	v_and_b32_e32 v11, 0xffff0000, v11
	v_add_f32_e32 v4, v4, v18
	v_lshlrev_b32_e32 v19, 16, v12
	v_add_f32_e32 v4, v4, v11
	v_and_b32_e32 v12, 0xffff0000, v12
	v_add_f32_e32 v4, v4, v19
	v_lshlrev_b32_e32 v20, 16, v13
	v_add_f32_e32 v4, v4, v12
	v_and_b32_e32 v13, 0xffff0000, v13
	v_add_f32_e32 v4, v4, v20
	v_add_f32_e32 v4, v4, v13
	s_waitcnt lgkmcnt(0)
	s_nop 1
	v_add_f32_dpp v4, v4, v4 quad_perm:[1,0,3,2] row_mask:0xf bank_mask:0xf
	s_nop 1
	v_add_f32_dpp v4, v4, v4 quad_perm:[2,3,0,1] row_mask:0xf bank_mask:0xf
	s_nop 1
	v_add_f32_dpp v4, v4, v4 row_half_mirror row_mask:0xf bank_mask:0xf
	s_nop 1
	v_add_f32_dpp v4, v4, v4 row_mirror row_mask:0xf bank_mask:0xf
	s_nop 1
	v_add_f32_dpp v4, v4, v4 row_bcast:15 row_mask:0xa bank_mask:0xf
	s_nop 1
	v_add_f32_dpp v4, v4, v4 row_bcast:31 row_mask:0xc bank_mask:0xf
	s_nop 1
	v_readlane_b32 s100, v4, 63
	s_nop 1
	v_mov_b32_e32 v4, s100
	v_fmac_f32_e32 v6, 0xba800000, v4
	v_fmac_f32_e32 v5, 0xba800000, v4
	v_mul_f32_e32 v6, v6, v6
	v_fmac_f32_e32 v14, 0xba800000, v4
	v_fmac_f32_e32 v6, v5, v5
	v_fmac_f32_e32 v7, 0xba800000, v4
	v_fmac_f32_e32 v6, v14, v14
	v_fmac_f32_e32 v15, 0xba800000, v4
	v_fmac_f32_e32 v6, v7, v7
	v_fmac_f32_e32 v8, 0xba800000, v4
	v_fmac_f32_e32 v6, v15, v15
	v_fmac_f32_e32 v16, 0xba800000, v4
	v_fmac_f32_e32 v6, v8, v8
	v_fmac_f32_e32 v9, 0xba800000, v4
	v_fmac_f32_e32 v6, v16, v16
	v_fmac_f32_e32 v17, 0xba800000, v4
	v_fmac_f32_e32 v6, v9, v9
	v_fmac_f32_e32 v10, 0xba800000, v4
	v_fmac_f32_e32 v6, v17, v17
	v_fmac_f32_e32 v18, 0xba800000, v4
	v_fmac_f32_e32 v6, v10, v10
	v_fmac_f32_e32 v11, 0xba800000, v4
	v_fmac_f32_e32 v6, v18, v18
	v_fmac_f32_e32 v19, 0xba800000, v4
	v_fmac_f32_e32 v6, v11, v11
	v_fmac_f32_e32 v12, 0xba800000, v4
	v_fmac_f32_e32 v6, v19, v19
	v_fmac_f32_e32 v20, 0xba800000, v4
	v_fmac_f32_e32 v6, v12, v12
	v_fmac_f32_e32 v6, v20, v20
	v_fmac_f32_e32 v13, 0xba800000, v4
	v_fmac_f32_e32 v6, v13, v13
	ds_bpermute_b32 v5, v47, v6
	s_waitcnt lgkmcnt(0)
	v_add_f32_e32 v5, v6, v5
	ds_bpermute_b32 v6, v120, v5
	s_waitcnt lgkmcnt(0)
	v_add_f32_e32 v5, v5, v6
	ds_bpermute_b32 v6, v121, v5
	s_waitcnt lgkmcnt(0)
	v_add_f32_e32 v5, v5, v6
	ds_bpermute_b32 v6, v122, v5
	s_waitcnt lgkmcnt(0)
	v_add_f32_e32 v5, v5, v6
	ds_bpermute_b32 v6, v123, v5
	s_waitcnt lgkmcnt(0)
	v_add_f32_e32 v5, v5, v6
	ds_bpermute_b32 v6, v124, v5
	s_and_saveexec_b64 s[8:9], s[4:5]
	s_cbranch_execz .LBB0_908
	s_waitcnt lgkmcnt(0)
	v_add_f32_e32 v5, v5, v6
	v_fmamk_f32 v5, v5, 0x3a800000, v138
	v_mul_f32_e32 v6, 0x4b800000, v5
	v_cmp_gt_f32_e32 vcc, s59, v5
	v_mul_f32_e32 v4, 0x3a800000, v4
	s_nop 0
	v_cndmask_b32_e32 v5, v5, v6, vcc
	v_rsq_f32_e32 v5, v5
	s_nop 0
	v_mul_f32_e32 v6, 0x45800000, v5
	v_cndmask_b32_e32 v5, v5, v6, vcc
	ds_write_b64 v0, v[4:5] offset:8
	s_branch .LBB0_908
